# 4-workgroup clique barriers (counter + L1 invalidate) only at the three WAR-safe row-local seams per layer; other seams full grid barriers
# baseline (speedup 1.0000x reference)
; __device__ __forceinline__ unsigned xb_ld(unsigned* p)              { return __hip_atomic_load(p, __ATOMIC_RELAXED, __HIP_MEMORY_SCOPE_AGENT); }
; __device__ __forceinline__ unsigned xb_add(unsigned* p, unsigned v) { return __hip_atomic_fetch_add(p, v, __ATOMIC_RELAXED, __HIP_MEMORY_SCOPE_AGENT); }
; #define XB_SPIN(cond, bar) do { unsigned _sp = 0; while (cond) { __builtin_amdgcn_s_sleep(1); \
;     if ((++_sp & 255u) == 0u) { if (xb_ld(&(bar)[XB_TMO])) break; if (_sp > XB_SPIN_CAP) { atomicAdd(&(bar)[XB_TMO], 1u); break; } } } } while (0)
; #define GSYNC() do { XcdBarrier xb_; xb_.bar = (unsigned*)(KARGS()->ws + WS_CTL) + 1024; xb_.x = xb_xcc_id(); xb_.st = (volatile LAS unsigned*)(lds + LDS_XB); xcd_barrier(xb_); } while (0)
; __device__ __forceinline__ void xcd_barrier(const XcdBarrier& b) {
;     asm volatile("s_waitcnt vmcnt(0)" ::: "memory");
;     __syncthreads();
;     if (threadIdx.x == 0) {
;         unsigned* bar = b.bar;
;         __builtin_amdgcn_s_waitcnt(0);
;         unsigned nloc = b.st[0], nx = b.st[1];
;         if (nloc == 0u) { xcd_barrier_complete(bar, b.x, nloc, nx); b.st[0] = nloc; b.st[1] = nx; }
;         const unsigned old = xb_add(&bar[XB_XSUB(b.x)], 1u);
;         const unsigned gen = old / nloc;
;         if (old + 1u == (gen + 1u) * nloc) {
;             __builtin_amdgcn_fence(__ATOMIC_RELEASE, "agent");
;             asm volatile("s_waitcnt vmcnt(0)" ::: "memory");
;             const unsigned og = xb_add(&bar[XB_TOP], 1u);
;             const unsigned tg = og / nx;
;             if (og + 1u == (tg + 1u) * nx) xb_add(&bar[XB_TOPGEN], 1u);
;             else XB_SPIN(xb_ld(&bar[XB_TOPGEN]) == tg, bar);
;             __builtin_amdgcn_fence(__ATOMIC_ACQUIRE, "agent");
;             xb_add(&bar[XB_XGEN(b.x)], 1u);
;             asm volatile("s_waitcnt vmcnt(0)" ::: "memory");
;         } else {
;             XB_SPIN(xb_ld(&bar[XB_XGEN(b.x)]) == gen, bar);
;             __builtin_amdgcn_fence(__ATOMIC_ACQUIRE, "agent");
;             asm volatile("s_waitcnt vmcnt(0)" ::: "memory");
;         }
;     }
;     __syncthreads();
; }
; __global__ void __launch_bounds__(512, 2) fwd_kernel(Args a) {
;     ...
;         GSYNC();
.LBB0_535:
	s_mov_b64 s[8:9], s[0:1]
	s_getreg_b32 s2, hwreg(HW_REG_XCC_ID, 0, 4)
	s_waitcnt vmcnt(0)
	v_readlane_b32 s6, v255, 0
	v_readlane_b32 s7, v255, 1
	s_waitcnt vmcnt(0)
	s_barrier
	v_readlane_b32 s4, v255, 40
	s_nop 1
	s_cmp_eq_u32 s4, 0
	s_cbranch_scc1 .Lfs0
	s_and_saveexec_b64 s[4:5], s[6:7]
	s_cbranch_execz .Lfe0
	s_load_dwordx2 s[8:9], s[0:1], 0x128
	v_readlane_b32 s10, v255, 41
	v_readlane_b32 s11, v255, 8
	s_nop 1
	s_and_b32 s11, s11, 63
	s_lshl_b32 s11, s11, 7
	s_addk_i32 s11, 0x6200
	v_mov_b32_e32 v2, 0
	v_mov_b32_e32 v3, 1
	s_add_i32 s10, s10, 1
	s_lshl_b32 s10, s10, 2
	s_waitcnt lgkmcnt(0)
	s_add_u32 s8, s8, s11
	s_addc_u32 s9, s9, 0
	global_atomic_add v2, v3, s[8:9]

; __device__ __forceinline__ unsigned xb_ld(unsigned* p)              { return __hip_atomic_load(p, __ATOMIC_RELAXED, __HIP_MEMORY_SCOPE_AGENT); }
; __device__ __forceinline__ unsigned xb_add(unsigned* p, unsigned v) { return __hip_atomic_fetch_add(p, v, __ATOMIC_RELAXED, __HIP_MEMORY_SCOPE_AGENT); }
; #define XB_SPIN(cond, bar) do { unsigned _sp = 0; while (cond) { __builtin_amdgcn_s_sleep(1); \
;     if ((++_sp & 255u) == 0u) { if (xb_ld(&(bar)[XB_TMO])) break; if (_sp > XB_SPIN_CAP) { atomicAdd(&(bar)[XB_TMO], 1u); break; } } } } while (0)
; #define GSYNC() do { XcdBarrier xb_; xb_.bar = (unsigned*)(KARGS()->ws + WS_CTL) + 1024; xb_.x = xb_xcc_id(); xb_.st = (volatile LAS unsigned*)(lds + LDS_XB); xcd_barrier(xb_); } while (0)
; __device__ __forceinline__ void xcd_barrier(const XcdBarrier& b) {
;     asm volatile("s_waitcnt vmcnt(0)" ::: "memory");
;     __syncthreads();
;     if (threadIdx.x == 0) {
;         unsigned* bar = b.bar;
;         __builtin_amdgcn_s_waitcnt(0);
;         unsigned nloc = b.st[0], nx = b.st[1];
;         if (nloc == 0u) { xcd_barrier_complete(bar, b.x, nloc, nx); b.st[0] = nloc; b.st[1] = nx; }
;         const unsigned old = xb_add(&bar[XB_XSUB(b.x)], 1u);
;         const unsigned gen = old / nloc;
;         if (old + 1u == (gen + 1u) * nloc) {
;             __builtin_amdgcn_fence(__ATOMIC_RELEASE, "agent");
;             asm volatile("s_waitcnt vmcnt(0)" ::: "memory");
;             const unsigned og = xb_add(&bar[XB_TOP], 1u);
;             const unsigned tg = og / nx;
;             if (og + 1u == (tg + 1u) * nx) xb_add(&bar[XB_TOPGEN], 1u);
;             else XB_SPIN(xb_ld(&bar[XB_TOPGEN]) == tg, bar);
;             __builtin_amdgcn_fence(__ATOMIC_ACQUIRE, "agent");
;             xb_add(&bar[XB_XGEN(b.x)], 1u);
;             asm volatile("s_waitcnt vmcnt(0)" ::: "memory");
;         } else {
;             XB_SPIN(xb_ld(&bar[XB_XGEN(b.x)]) == gen, bar);
;             __builtin_amdgcn_fence(__ATOMIC_ACQUIRE, "agent");
;             asm volatile("s_waitcnt vmcnt(0)" ::: "memory");
;         }
;     }
;     __syncthreads();
; }
; __global__ void __launch_bounds__(512, 2) fwd_kernel(Args a) {
;     ...
;         GSYNC();
.LBB0_630:
	s_mov_b64 s[8:9], s[0:1]
	s_getreg_b32 s2, hwreg(HW_REG_XCC_ID, 0, 4)
	s_waitcnt vmcnt(0)
	s_waitcnt lgkmcnt(0)
	v_readlane_b32 s6, v255, 0
	v_readlane_b32 s7, v255, 1
	s_barrier
	v_readlane_b32 s4, v255, 40
	s_nop 1
	s_cmp_eq_u32 s4, 0
	s_branch .Lfs1
	s_and_saveexec_b64 s[4:5], s[6:7]
	s_cbranch_execz .Lfe1
	s_load_dwordx2 s[8:9], s[0:1], 0x128
	v_readlane_b32 s10, v255, 41
	v_readlane_b32 s11, v255, 8
	s_nop 1
	s_and_b32 s11, s11, 63
	s_lshl_b32 s11, s11, 7
	s_addk_i32 s11, 0x6200
	v_mov_b32_e32 v2, 0
	v_mov_b32_e32 v3, 1
	s_add_i32 s10, s10, 1
	s_lshl_b32 s10, s10, 2
	s_waitcnt lgkmcnt(0)
	s_add_u32 s8, s8, s11
	s_addc_u32 s9, s9, 0
	global_atomic_add v2, v3, s[8:9]

; __device__ __forceinline__ unsigned xb_ld(unsigned* p)              { return __hip_atomic_load(p, __ATOMIC_RELAXED, __HIP_MEMORY_SCOPE_AGENT); }
; __device__ __forceinline__ unsigned xb_add(unsigned* p, unsigned v) { return __hip_atomic_fetch_add(p, v, __ATOMIC_RELAXED, __HIP_MEMORY_SCOPE_AGENT); }
; #define XB_SPIN(cond, bar) do { unsigned _sp = 0; while (cond) { __builtin_amdgcn_s_sleep(1); \
;     if ((++_sp & 255u) == 0u) { if (xb_ld(&(bar)[XB_TMO])) break; if (_sp > XB_SPIN_CAP) { atomicAdd(&(bar)[XB_TMO], 1u); break; } } } } while (0)
; #define GSYNC() do { XcdBarrier xb_; xb_.bar = (unsigned*)(KARGS()->ws + WS_CTL) + 1024; xb_.x = xb_xcc_id(); xb_.st = (volatile LAS unsigned*)(lds + LDS_XB); xcd_barrier(xb_); } while (0)
; __device__ __forceinline__ void xcd_barrier(const XcdBarrier& b) {
;     asm volatile("s_waitcnt vmcnt(0)" ::: "memory");
;     __syncthreads();
;     if (threadIdx.x == 0) {
;         unsigned* bar = b.bar;
;         __builtin_amdgcn_s_waitcnt(0);
;         unsigned nloc = b.st[0], nx = b.st[1];
;         if (nloc == 0u) { xcd_barrier_complete(bar, b.x, nloc, nx); b.st[0] = nloc; b.st[1] = nx; }
;         const unsigned old = xb_add(&bar[XB_XSUB(b.x)], 1u);
;         const unsigned gen = old / nloc;
;         if (old + 1u == (gen + 1u) * nloc) {
;             __builtin_amdgcn_fence(__ATOMIC_RELEASE, "agent");
;             asm volatile("s_waitcnt vmcnt(0)" ::: "memory");
;             const unsigned og = xb_add(&bar[XB_TOP], 1u);
;             const unsigned tg = og / nx;
;             if (og + 1u == (tg + 1u) * nx) xb_add(&bar[XB_TOPGEN], 1u);
;             else XB_SPIN(xb_ld(&bar[XB_TOPGEN]) == tg, bar);
;             __builtin_amdgcn_fence(__ATOMIC_ACQUIRE, "agent");
;             xb_add(&bar[XB_XGEN(b.x)], 1u);
;             asm volatile("s_waitcnt vmcnt(0)" ::: "memory");
;         } else {
;             XB_SPIN(xb_ld(&bar[XB_XGEN(b.x)]) == gen, bar);
;             __builtin_amdgcn_fence(__ATOMIC_ACQUIRE, "agent");
;             asm volatile("s_waitcnt vmcnt(0)" ::: "memory");
;         }
;     }
;     __syncthreads();
; }
; __global__ void __launch_bounds__(512, 2) fwd_kernel(Args a) {
;     ...
;         GSYNC();
.LBB0_1525:
	s_mov_b64 s[8:9], s[0:1]
	s_getreg_b32 s2, hwreg(HW_REG_XCC_ID, 0, 4)
	s_waitcnt vmcnt(0)
	v_readlane_b32 s6, v255, 0
	v_readlane_b32 s7, v255, 1
	s_waitcnt lgkmcnt(0)
	s_barrier
	v_readlane_b32 s4, v255, 40
	s_nop 1
	s_cmp_eq_u32 s4, 0
	s_branch .Lfs2
	s_and_saveexec_b64 s[4:5], s[6:7]
	s_cbranch_execz .Lfe2
	s_load_dwordx2 s[8:9], s[0:1], 0x128
	v_readlane_b32 s10, v255, 41
	v_readlane_b32 s11, v255, 8
	s_nop 1
	s_and_b32 s11, s11, 63
	s_lshl_b32 s11, s11, 7
	s_addk_i32 s11, 0x6200
	v_mov_b32_e32 v2, 0
	v_mov_b32_e32 v3, 1
	s_add_i32 s10, s10, 1
	s_lshl_b32 s10, s10, 2
	s_waitcnt lgkmcnt(0)
	s_add_u32 s8, s8, s11
	s_addc_u32 s9, s9, 0
	global_atomic_add v2, v3, s[8:9]

; __device__ __forceinline__ unsigned xb_ld(unsigned* p)              { return __hip_atomic_load(p, __ATOMIC_RELAXED, __HIP_MEMORY_SCOPE_AGENT); }
; __device__ __forceinline__ unsigned xb_add(unsigned* p, unsigned v) { return __hip_atomic_fetch_add(p, v, __ATOMIC_RELAXED, __HIP_MEMORY_SCOPE_AGENT); }
; #define XB_SPIN(cond, bar) do { unsigned _sp = 0; while (cond) { __builtin_amdgcn_s_sleep(1); \
;     if ((++_sp & 255u) == 0u) { if (xb_ld(&(bar)[XB_TMO])) break; if (_sp > XB_SPIN_CAP) { atomicAdd(&(bar)[XB_TMO], 1u); break; } } } } while (0)
; #define GSYNC() do { XcdBarrier xb_; xb_.bar = (unsigned*)(KARGS()->ws + WS_CTL) + 1024; xb_.x = xb_xcc_id(); xb_.st = (volatile LAS unsigned*)(lds + LDS_XB); xcd_barrier(xb_); } while (0)
; __device__ __forceinline__ void xcd_barrier(const XcdBarrier& b) {
;     asm volatile("s_waitcnt vmcnt(0)" ::: "memory");
;     __syncthreads();
;     if (threadIdx.x == 0) {
;         unsigned* bar = b.bar;
;         __builtin_amdgcn_s_waitcnt(0);
;         unsigned nloc = b.st[0], nx = b.st[1];
;         if (nloc == 0u) { xcd_barrier_complete(bar, b.x, nloc, nx); b.st[0] = nloc; b.st[1] = nx; }
;         const unsigned old = xb_add(&bar[XB_XSUB(b.x)], 1u);
;         const unsigned gen = old / nloc;
;         if (old + 1u == (gen + 1u) * nloc) {
;             __builtin_amdgcn_fence(__ATOMIC_RELEASE, "agent");
;             asm volatile("s_waitcnt vmcnt(0)" ::: "memory");
;             const unsigned og = xb_add(&bar[XB_TOP], 1u);
;             const unsigned tg = og / nx;
;             if (og + 1u == (tg + 1u) * nx) xb_add(&bar[XB_TOPGEN], 1u);
;             else XB_SPIN(xb_ld(&bar[XB_TOPGEN]) == tg, bar);
;             __builtin_amdgcn_fence(__ATOMIC_ACQUIRE, "agent");
;             xb_add(&bar[XB_XGEN(b.x)], 1u);
;             asm volatile("s_waitcnt vmcnt(0)" ::: "memory");
;         } else {
;             XB_SPIN(xb_ld(&bar[XB_XGEN(b.x)]) == gen, bar);
;             __builtin_amdgcn_fence(__ATOMIC_ACQUIRE, "agent");
;             asm volatile("s_waitcnt vmcnt(0)" ::: "memory");
;         }
;     }
;     __syncthreads();
; }
; __global__ void __launch_bounds__(512, 2) fwd_kernel(Args a) {
;     ...
;         GSYNC();
.LBB0_2010:
	s_mov_b64 s[8:9], s[0:1]
	s_getreg_b32 s2, hwreg(HW_REG_XCC_ID, 0, 4)
	s_waitcnt vmcnt(0)
	v_readlane_b32 s6, v255, 0
	v_readlane_b32 s7, v255, 1
	s_waitcnt vmcnt(0) lgkmcnt(0)
	s_barrier
	v_readlane_b32 s4, v255, 40
	s_nop 1
	s_cmp_eq_u32 s4, 0
	s_cbranch_scc1 .Lfs5
	s_and_saveexec_b64 s[4:5], s[6:7]
	s_cbranch_execz .Lfe5
	s_load_dwordx2 s[8:9], s[0:1], 0x128
	v_readlane_b32 s10, v255, 41
	v_readlane_b32 s11, v255, 8
	s_nop 1
	s_and_b32 s11, s11, 63
	s_lshl_b32 s11, s11, 7
	s_addk_i32 s11, 0x6200
	v_mov_b32_e32 v2, 0
	v_mov_b32_e32 v3, 1
	s_add_i32 s10, s10, 1
	s_lshl_b32 s10, s10, 2
	s_waitcnt lgkmcnt(0)
	s_add_u32 s8, s8, s11
	s_addc_u32 s9, s9, 0
	global_atomic_add v2, v3, s[8:9]
